# bias2 rows of batches 2,3 computed by batches 0,1 (work shifted to the batches that finish early)
# speedup vs baseline: 1.0102x; 1.0102x over previous
.LBB0_346:
	s_mov_b32 s101, 0
	s_lshr_b32 s4, s83, 6
	s_cmp_ge_u32 s4, 2
	s_cbranch_scc1 .LBB0_357

.LBB0_356:
	v_readlane_b32 s68, v251, 22
	s_mov_b64 s[70:71], s[24:25]
	s_mov_b32 s96, s14
	v_readlane_b32 s69, v251, 23
	s_mov_b32 s72, s15
	s_cmp_lg_u32 s101, 0
	s_cbranch_scc1 .LBB0_357
	s_mov_b32 s101, 1
	v_readlane_b32 s83, v251, 26
	s_nop 3
	s_add_i32 s83, s83, 0x80
	s_branch .Lb2_again
